# GEMM phase prologue: first tile computed directly on the 256-workgroup grid; workspace pointer fetched once before the phase loop instead of an s_load per phase
# speedup vs baseline: 1.0099x; 1.0028x over previous
; #define LAS __attribute__((address_space(3)))
; __global__ void __launch_bounds__(512, 2) fwd_kernel(Args A_unused) {
;     CA* const P0 = (CA*)__builtin_amdgcn_kernarg_segment_ptr();
;     extern __shared__ __attribute__((aligned(16))) unsigned char lds_raw[];
;     LAS unsigned char* lds = (LAS unsigned char*)lds_raw;
;     cg::grid_group grid = cg::this_grid();
;     const int ph_lo = P0->ph_lo, ph_hi = P0->ph_hi;
;     if (threadIdx.x < 16) ((LAS unsigned*)(lds + LDS_MAIN))[threadIdx.x] = 0u;
;     __syncthreads();
;     XcdBarrier xbar = xcd_barrier_post((unsigned*)(P0->ws + WS_XBAR), (volatile LAS unsigned*)(lds + LDS_MAIN + 16));
;     for (int ph = ph_lo; ph < ph_hi; ++ph) {
;         CA* P = P0; asm volatile("" : "+s"(P)); CA& A = *P;
;         bf16_t* XN = (bf16_t*)(A.ws + WS_XN); bf16_t* ACT = (bf16_t*)(A.ws + WS_ACT); bf16_t* Zp = (bf16_t*)(A.ws + WS_Z); bf16_t* MIXp = (bf16_t*)(A.ws + WS_MIX);
.LBB0_6:
	v_readlane_b32 s10, v238, 6
	s_lshl_b32 s7, s92, 3
	s_lshl_b32 s4, s10, 3
	s_cmpk_eq_i32 s10, 0x100
	v_readlane_b32 s11, v238, 7
	v_writelane_b32 v238, s4, 10
	s_cselect_b64 s[4:5], -1, 0
	v_writelane_b32 v238, s4, 11
	s_movk_i32 s6, 0x2880
	v_lshrrev_b32_e32 v1, 20, v0
	v_writelane_b32 v238, s5, 12
	s_and_b64 s[4:5], s[4:5], exec
	s_cselect_b32 s4, s6, 0x5100
	v_writelane_b32 v238, s4, 13
	s_ashr_i32 s4, s92, 31
	v_writelane_b32 v238, s4, 14
	s_lshr_b32 s4, s4, 29
	s_add_i32 s4, s92, s4
	s_ashr_i32 s9, s4, 3
	s_and_b32 s4, s4, -8
	s_sub_i32 s12, s92, s4
	s_ashr_i32 s4, s10, 31
	s_cmpk_lt_i32 s92, 0x100
	v_writelane_b32 v238, s4, 15
	s_cselect_b64 s[4:5], -1, 0
	v_writelane_b32 v238, s4, 16
	v_lshrrev_b32_e32 v0, 10, v0
	v_or_b32_e32 v0, v0, v1
	v_writelane_b32 v238, s5, 17
	s_lshl_b32 s5, s12, 5
	s_cmpk_lt_u32 s92, 0x80
	s_cselect_b64 s[14:15], -1, 0
	v_writelane_b32 v238, s14, 18
	s_add_i32 s4, s7, 0xfffffc00
	s_cmpk_gt_u32 s92, 0xbf
	v_writelane_b32 v238, s15, 19
	v_writelane_b32 v238, s4, 20
	s_cselect_b64 s[14:15], -1, 0
	v_writelane_b32 v238, s14, 21
	s_add_i32 s4, s7, 0xfffffa00
	s_cmp_lt_u32 s92, 16
	v_writelane_b32 v238, s15, 22
	v_writelane_b32 v238, s7, 23
	v_writelane_b32 v238, s4, 24
	s_cselect_b64 s[6:7], -1, 0
	v_writelane_b32 v238, s6, 25
	s_and_b32 s4, s92, 3
	v_mbcnt_lo_u32_b32 v2, -1, 0
	v_writelane_b32 v238, s7, 26
	s_lshl_b32 s6, s92, 10
	s_and_b32 s14, s6, 0x3000
	s_lshl_b32 s6, s92, 14
	v_writelane_b32 v238, s6, 27
	v_mov_b32_e32 v216, 0x358637bd
	v_readlane_b32 s6, v238, 0
	v_readlane_b32 s7, v238, 1
	s_cmp_lt_i32 s6, 0
	s_cselect_b64 s[6:7], -1, 0
	v_writelane_b32 v238, s6, 28
	v_mov_b32_e32 v217, 1
	v_mov_b32_e32 v218, 0x3f4ccccd
	v_writelane_b32 v238, s7, 29
	s_add_u32 s6, s0, 0x4200
	s_addc_u32 s7, s1, 0
	v_writelane_b32 v238, s6, 30
	v_mov_b32_e32 v219, 0x260
	v_bfrev_b32_e32 v220, 0.5
	v_writelane_b32 v238, s7, 31
	s_add_u32 s6, s0, 0x4400
	s_addc_u32 s7, s1, 0
	v_writelane_b32 v238, s6, 32
	v_mov_b32_e32 v221, 0x7f800000
	v_mbcnt_hi_u32_b32 v222, -1, v2
	v_writelane_b32 v238, s7, 33
	s_add_u32 s6, s0, 0x4500
	s_addc_u32 s7, s1, 0
	v_writelane_b32 v238, s6, 34
	v_mov_b32_e32 v223, 2
	v_mov_b32_e32 v224, 0x1200
	v_writelane_b32 v238, s7, 35
	s_add_u32 s6, s0, 0x4600
	s_addc_u32 s7, s1, 0
	v_writelane_b32 v238, s6, 36
	v_mov_b32_e32 v225, 0xf149f2ca
	v_mov_b32_e32 v226, 0x50000
	v_writelane_b32 v238, s7, 37
	s_add_u32 s6, s0, 0x4700
	s_addc_u32 s7, s1, 0
	v_writelane_b32 v238, s6, 38
	s_movk_i32 s33, 0x80
	s_movk_i32 s93, 0x1400
	v_writelane_b32 v238, s7, 39
	s_add_u32 s6, s0, 0x4800
	s_addc_u32 s7, s1, 0
	v_writelane_b32 v238, s6, 40
	s_movk_i32 s21, 0x7fff
	s_mov_b32 s94, 0x3b800000
	v_writelane_b32 v238, s7, 41
	s_add_u32 s6, s0, 0x4900
	s_addc_u32 s7, s1, 0
	v_writelane_b32 v238, s6, 42
	s_mov_b32 s96, 0x358637bd
	s_mov_b32 s36, 0x3f803f80
	v_writelane_b32 v238, s7, 43
	s_add_u32 s6, s0, 0x4a00
	s_addc_u32 s7, s1, 0
	v_writelane_b32 v238, s6, 44
	s_nop 1
	v_writelane_b32 v238, s7, 45
	s_add_u32 s6, s0, 0x4b00
	s_addc_u32 s7, s1, 0
	v_writelane_b32 v238, s6, 46
	s_nop 1
	v_writelane_b32 v238, s7, 47
	s_add_u32 s6, s0, 0x4c00
	s_addc_u32 s7, s1, 0
	v_writelane_b32 v238, s6, 48
	s_nop 1
	v_writelane_b32 v238, s7, 49
	s_add_u32 s6, s0, 0x4d00
	s_addc_u32 s7, s1, 0
	v_writelane_b32 v238, s6, 50
	s_nop 1
	v_writelane_b32 v238, s7, 51
	s_add_u32 s6, s0, 0x4e00
	s_addc_u32 s7, s1, 0
	v_writelane_b32 v238, s6, 52
	s_nop 1
	v_writelane_b32 v238, s7, 53
	s_add_u32 s6, s0, 0x4f00
	s_addc_u32 s7, s1, 0
	v_writelane_b32 v238, s6, 54
	s_nop 1
	v_writelane_b32 v238, s7, 55
	s_add_u32 s6, s0, 0x5000
	s_addc_u32 s7, s1, 0
	v_writelane_b32 v238, s6, 56
	s_nop 1
	v_writelane_b32 v238, s7, 57
	s_add_u32 s6, s0, 0x5100
	s_addc_u32 s7, s1, 0
	v_writelane_b32 v238, s6, 58
	s_nop 1
	v_writelane_b32 v238, s7, 59
	s_add_u32 s6, s0, 0x5200
	s_addc_u32 s7, s1, 0
	v_writelane_b32 v238, s6, 60
	s_nop 1
	v_writelane_b32 v238, s7, 61
	s_add_u32 s6, s0, 0x5300
	s_addc_u32 s7, s1, 0
	v_writelane_b32 v238, s6, 62
	s_cmp_eq_u32 s8, 15
	s_nop 0
	v_writelane_b32 v238, s7, 63
	s_cselect_b64 s[6:7], -1, 0
	v_writelane_b32 v237, s6, 0
	s_cmp_eq_u32 s8, 14
	s_nop 0
	v_writelane_b32 v237, s7, 1
	s_cselect_b64 s[6:7], -1, 0
	v_writelane_b32 v237, s6, 2
	s_cmp_eq_u32 s8, 13
	s_nop 0
	v_writelane_b32 v237, s7, 3
	s_cselect_b64 s[6:7], -1, 0
	v_writelane_b32 v237, s6, 4
	s_cmp_eq_u32 s8, 12
	s_nop 0
	v_writelane_b32 v237, s7, 5
	s_cselect_b64 s[6:7], -1, 0
	v_writelane_b32 v237, s6, 6
	s_cmp_eq_u32 s8, 11
	s_nop 0
	v_writelane_b32 v237, s7, 7
	s_cselect_b64 s[6:7], -1, 0
	v_writelane_b32 v237, s6, 8
	s_cmp_eq_u32 s8, 10
	s_nop 0
	v_writelane_b32 v237, s7, 9
	s_cselect_b64 s[6:7], -1, 0
	v_writelane_b32 v237, s6, 10
	s_cmp_eq_u32 s8, 9
	s_nop 0
	v_writelane_b32 v237, s7, 11
	s_cselect_b64 s[6:7], -1, 0
	v_writelane_b32 v237, s6, 12
	s_cmp_eq_u32 s8, 8
	s_nop 0
	v_writelane_b32 v237, s7, 13
	s_cselect_b64 s[6:7], -1, 0
	v_writelane_b32 v237, s6, 14
	s_cmp_eq_u32 s8, 7
	s_nop 0
	v_writelane_b32 v237, s7, 15
	s_cselect_b64 s[6:7], -1, 0
	v_writelane_b32 v237, s6, 16
	s_cmp_eq_u32 s8, 6
	s_nop 0
	v_writelane_b32 v237, s7, 17
	s_cselect_b64 s[6:7], -1, 0
	v_writelane_b32 v237, s6, 18
	s_cmp_eq_u32 s8, 5
	s_nop 0
	v_writelane_b32 v237, s7, 19
	s_cselect_b64 s[6:7], -1, 0
	v_writelane_b32 v237, s6, 20
	s_cmp_eq_u32 s8, 4
	s_nop 0
	v_writelane_b32 v237, s7, 21
	s_cselect_b64 s[6:7], -1, 0
	v_writelane_b32 v237, s6, 22
	s_cmp_eq_u32 s8, 3
	s_nop 0
	v_writelane_b32 v237, s7, 23
	s_cselect_b64 s[6:7], -1, 0
	v_writelane_b32 v237, s6, 24
	s_cmp_eq_u32 s8, 2
	s_nop 0
	v_writelane_b32 v237, s7, 25
	s_cselect_b64 s[6:7], -1, 0
	v_writelane_b32 v237, s6, 26
	s_cmp_eq_u32 s8, 1
	s_nop 0
	v_writelane_b32 v237, s7, 27
	s_cselect_b64 s[6:7], -1, 0
	v_writelane_b32 v237, s6, 28
	s_cmp_eq_u32 s8, 0
	s_nop 0
	v_writelane_b32 v237, s7, 29
	s_cselect_b64 s[6:7], -1, 0
	v_writelane_b32 v237, s6, 30
	s_nop 1
	v_writelane_b32 v237, s7, 31
	s_lshl_b32 s6, s8, 8
	s_add_u32 s2, s2, s6
	s_addc_u32 s3, s3, 0
	s_add_u32 s6, s2, 0x1400
	s_addc_u32 s7, s3, 0
	v_writelane_b32 v237, s6, 32
	s_add_u32 s2, s2, 0x2400
	s_addc_u32 s3, s3, 0
	v_writelane_b32 v237, s7, 33
	v_writelane_b32 v237, s2, 34
	s_mov_b32 s7, 0
	s_mov_b32 s15, s7
	v_writelane_b32 v237, s3, 35
	s_add_u32 s2, s0, 0x7400
	s_addc_u32 s3, s1, 0
	v_writelane_b32 v237, s2, 36
	s_add_u32 s0, s0, 0x7500
	s_addc_u32 s1, s1, 0
	v_writelane_b32 v237, s3, 37
	v_readlane_b32 s2, v238, 2
	v_writelane_b32 v237, s0, 38
	v_readlane_b32 s3, v238, 3
	s_cmp_lt_i32 s12, 0
	v_writelane_b32 v237, s1, 39
	s_load_dword s1, s[2:3], 0xe0
	s_movk_i32 s0, 0x3ff
	v_and_or_b32 v1, v0, s0, v179
	s_mul_i32 s0, s11, s10
	s_mov_b32 s6, s92
	s_waitcnt lgkmcnt(0)
; #define LAS __attribute__((address_space(3)))
; __global__ void __launch_bounds__(512, 2) fwd_kernel(Args A_unused) {
;     CA* const P0 = (CA*)__builtin_amdgcn_kernarg_segment_ptr();
;     extern __shared__ __attribute__((aligned(16))) unsigned char lds_raw[];
;     LAS unsigned char* lds = (LAS unsigned char*)lds_raw;
;     cg::grid_group grid = cg::this_grid();
;     const int ph_lo = P0->ph_lo, ph_hi = P0->ph_hi;
;     if (threadIdx.x < 16) ((LAS unsigned*)(lds + LDS_MAIN))[threadIdx.x] = 0u;
;     __syncthreads();
;     XcdBarrier xbar = xcd_barrier_post((unsigned*)(P0->ws + WS_XBAR), (volatile LAS unsigned*)(lds + LDS_MAIN + 16));
;     for (int ph = ph_lo; ph < ph_hi; ++ph) {
;         CA* P = P0; asm volatile("" : "+s"(P)); CA& A = *P;
;         bf16_t* XN = (bf16_t*)(A.ws + WS_XN); bf16_t* ACT = (bf16_t*)(A.ws + WS_ACT); bf16_t* Zp = (bf16_t*)(A.ws + WS_Z); bf16_t* MIXp = (bf16_t*)(A.ws + WS_MIX);
	s_mul_i32 s0, s0, s1
	v_writelane_b32 v237, s0, 40
	s_mul_i32 s0, s12, 33
	s_cselect_b32 s0, s0, s5
	s_add_i32 s0, s0, s9
	s_ashr_i32 s1, s0, 31
	s_lshr_b32 s1, s1, 27
	s_add_i32 s1, s0, s1
	s_and_b32 s2, s1, 0xffe0
	s_sub_i32 s0, s0, s2
	s_bfe_i32 s2, s0, 0x80000
	s_bfe_u32 s2, s2, 0x3000c
	s_add_i32 s2, s0, s2
	s_and_b32 s3, s2, 0xf8
	s_sub_i32 s0, s0, s3
	s_ashr_i32 s1, s1, 5
	v_writelane_b32 v237, s9, 41
	s_lshl_b32 s1, s1, 3
	s_sext_i32_i8 s0, s0
	v_writelane_b32 v237, s14, 42
	s_add_i32 s0, s1, s0
	s_ashr_i32 s3, s0, 4
	v_writelane_b32 v237, s15, 43
	s_ashr_i32 s1, s0, 31
	v_writelane_b32 v237, s3, 44
	s_lshl_b32 s3, s0, 8
	s_bfe_i32 s2, s2, 0x80000
	v_writelane_b32 v237, s3, 45
	s_lshl_b64 s[0:1], s[0:1], 6
	s_sext_i32_i16 s2, s2
	v_writelane_b32 v237, s0, 46
	s_mov_b32 s5, s7
	v_mov_b32_e32 v0, 0
	v_writelane_b32 v237, s1, 47
	s_lshl_b32 s0, s2, 5
	s_and_b32 s0, s0, 0xffffff00
	v_writelane_b32 v237, s0, 48
	s_lshl_b32 s0, s4, 2
	v_writelane_b32 v237, s0, 49
	v_writelane_b32 v237, s12, 50
	s_lshr_b32 s0, s12, 31
	v_writelane_b32 v237, s0, 51
	s_lshl_b32 s0, s92, 6
	v_writelane_b32 v237, s0, 52
	s_lshl_b32 s0, s10, 6
	v_writelane_b32 v237, s0, 53
	s_add_i32 s2, 0, 0x20010
	v_writelane_b32 v237, s2, 54
	s_add_i32 s2, 0, 0x20014
	v_writelane_b32 v237, s2, 55
	v_cmp_eq_u32_e64 s[2:3], 0, v1
	s_mov_b32 s0, 0x800000
	s_mov_b32 s1, 0x5040100
	v_writelane_b32 v237, s2, 56
	s_nop 1
	v_writelane_b32 v237, s3, 57
	v_writelane_b32 v237, s4, 58
	s_mov_b64 s[2:3], 0x80
	s_nop 0
	v_writelane_b32 v237, s5, 59
	s_lshl_b64 s[4:5], s[6:7], 2
	v_writelane_b32 v237, s4, 60
	s_nop 1
	v_writelane_b32 v237, s5, 61
	v_writelane_b32 v237, s92, 62
	v_readlane_b32 s4, v238, 2
	v_readlane_b32 s5, v238, 3
	s_nop 4
	s_load_dwordx2 s[4:5], s[4:5], 0xc8
	s_waitcnt lgkmcnt(0)
	v_writelane_b32 v236, s4, 1
	s_nop 1
	v_writelane_b32 v236, s5, 2
	s_branch .LBB0_10

; __device__ __forceinline__ int otid() { int t = (int)threadIdx.x; asm volatile("" : "+v"(t)); return t; }
; __device__ __forceinline__ void p1_phase(CA& A) {
;     const int tid = otid(), lane = tid & 63, wave = __builtin_amdgcn_readfirstlane(tid >> 6);
;     const int gw = blockIdx.x * 8 + wave, NGW = gridDim.x * 8;
;     const float* MOD = (const float*)(A.ws + WS_MOD);
;     bf16_t* XN = (bf16_t*)(A.ws + WS_XN);
;     for (int grp = gw; grp < M / 8; grp += NGW) {
; __global__ void __launch_bounds__(512, 2) fwd_kernel(Args A_unused) {
;     ...
;     for (int ph = ph_lo; ph < ph_hi; ++ph) {
;         CA* P = P0; asm volatile("" : "+s"(P)); CA& A = *P;
;         bf16_t* XN = (bf16_t*)(A.ws + WS_XN); bf16_t* ACT = (bf16_t*)(A.ws + WS_ACT); bf16_t* Zp = (bf16_t*)(A.ws + WS_Z); bf16_t* MIXp = (bf16_t*)(A.ws + WS_MIX);
;         const float* MOD = (const float*)(A.ws + WS_MOD);
;         if (ph == 0) { p0_prologue(A, lds); }
;         else if (ph == 1) { p1_phase(A); }
.LBB0_10:
	v_readlane_b32 s4, v238, 2
	v_readlane_b32 s5, v238, 3
	v_readlane_b32 s6, v238, 0
	v_writelane_b32 v237, s4, 63
	v_readlane_b32 s7, v238, 1
	s_waitcnt lgkmcnt(0)
	s_mov_b64 s[8:9], -1
	v_writelane_b32 v236, s5, 0
	s_cmp_lt_i32 s6, 1
	s_mov_b64 s[6:7], 0
	s_mov_b64 s[4:5], 0
	s_cbranch_scc1 .LBB0_24
	v_readlane_b32 s6, v238, 0
	v_readlane_b32 s7, v238, 1
	s_cmp_eq_u32 s6, 1
	s_mov_b64 s[6:7], -1
	s_cbranch_scc0 .LBB0_18
	v_mov_b32_e32 v1, v179
	v_readlane_b32 s7, v237, 62
	s_nop 1
	s_and_b32 s18, s7, 7
	s_lshl_b32 s18, s18, 5
	s_bfe_u32 s19, s7, 0x30003
	s_lshl_b32 s19, s19, 2
	s_add_i32 s18, s18, s19
	s_lshr_b32 s7, s7, 6
	s_add_i32 s7, s18, s7
	s_lshl_b32 s7, s7, 3
	v_readfirstlane_b32 s6, v1
	s_ashr_i32 s6, s6, 6
	s_add_i32 s10, s6, s7
	s_cmpk_gt_i32 s10, 0x7ff
	s_cbranch_scc1 .LBB0_17
	v_readlane_b32 s14, v237, 63
	v_readlane_b32 s15, v236, 0
	s_load_dwordx2 s[8:9], s[14:15], 0x0
	s_nop 0
	s_load_dwordx2 s[14:15], s[14:15], 0x20
	v_readlane_b32 s16, v236, 1
	v_lshlrev_b32_e32 v2, 2, v1
	v_and_b32_e32 v1, 63, v1
	v_readlane_b32 s17, v236, 2
	v_and_b32_e32 v2, 0xfc, v2
	v_lshlrev_b32_e32 v10, 3, v1
	v_mov_b32_e32 v11, v0
	s_add_u32 s11, s16, 0x10000
	v_lshlrev_b32_e32 v4, 2, v2
	v_mov_b32_e32 v5, v0
	v_lshl_add_u64 v[20:21], s[16:17], 0, v[10:11]
	v_lshlrev_b32_e32 v10, 4, v1
	s_addc_u32 s12, s17, 0
	s_waitcnt lgkmcnt(0)
	v_lshl_add_u64 v[18:19], s[14:15], 0, v[4:5]
	v_or_b32_e32 v4, 0x100, v2
	v_or_b32_e32 v6, 0x200, v2
	v_or_b32_e32 v8, 0x300, v2
	s_lshl_b32 s6, s6, 3
	s_lshl_b32 s7, s10, 3
	s_sub_i32 s7, s7, s6
	v_lshl_add_u64 v[10:11], s[8:9], 0, v[10:11]
	s_mov_b64 s[8:9], 0x800
	s_add_i32 s6, s7, s6
	v_lshl_add_u64 v[22:23], v[10:11], 0, s[8:9]
	v_lshlrev_b32_e32 v1, 2, v2
	v_lshlrev_b32_e32 v44, 2, v4
	v_lshlrev_b32_e32 v45, 2, v6
	v_lshlrev_b32_e32 v46, 2, v8

;     __host__ __device__ bool next(int i, Unit& u) const {
;         const long L = (long)i * G + c; if (L >= nwg) return false;
;         int wgid = (int)L; { const int q = nwg / NXCD, r = nwg % NXCD, xcd = wgid % NXCD, off = wgid / NXCD; wgid = (xcd < r ? xcd * (q + 1) : r * (q + 1) + (xcd - r) * q) + off; }
;         const int nig = WGM * nN, gid = wgid / nig, fm = gid * WGM, gsz = (nM - fm) < WGM ? (nM - fm) : WGM;
;         u.pm = fm + ((wgid % nig) % gsz); u.pn = (wgid % nig) / gsz; return true;
;     }
.LBB0_41:
	s_lshl_b32 s14, s15, 6
	v_mov_b32_e32 v14, v179
	s_cmp_lt_i32 s92, s14
	s_cselect_b64 s[4:5], -1, 0
	s_cmp_ge_i32 s92, s14
	v_readfirstlane_b32 s24, v14
	s_cbranch_scc1 .LBB0_46
	v_readlane_b32 s16, v238, 6
	s_and_b32 s17, s92, 7
	s_lshl_b32 s17, s17, 3
	s_bfe_u32 s31, s92, 0x30003
	s_cmpk_lg_i32 s16, 0x100
	s_cbranch_scc1 .Lmy_pro_slow
	s_add_i32 s31, s31, s17
	s_lshr_b32 s30, s92, 6
	s_branch .Lmy_pro_join
.Lmy_pro_slow:
	s_lshl_b32 s16, s15, 3
	v_cvt_f32_u32_e32 v1, s16
	v_readlane_b32 s17, v237, 51
	s_or_b32 s17, s16, s17
	s_sub_i32 s18, 0, s16
	v_rcp_iflag_f32_e32 v1, v1
	v_readlane_b32 s19, v237, 50
	s_mul_i32 s17, s17, s19
	v_readlane_b32 s19, v237, 41
	v_mul_f32_e32 v1, 0x4f7ffffe, v1
	v_cvt_u32_f32_e32 v1, v1
	s_add_i32 s17, s17, s19
	s_abs_i32 s25, s17
	s_ashr_i32 s19, s17, 31
	v_readfirstlane_b32 s26, v1
	s_mul_i32 s18, s18, s26
	s_mul_hi_u32 s18, s26, s18
	s_add_i32 s26, s26, s18
	s_mul_hi_u32 s18, s25, s26
	s_mul_i32 s26, s18, s16
	s_sub_i32 s25, s25, s26
	s_add_i32 s27, s18, 1
	s_sub_i32 s26, s25, s16
	s_cmp_ge_u32 s25, s16
	s_cselect_b32 s18, s27, s18
	s_cselect_b32 s25, s26, s25
	s_add_i32 s26, s18, 1
	s_cmp_ge_u32 s25, s16
	s_cselect_b32 s18, s26, s18
	s_xor_b32 s18, s18, s19
	s_sub_i32 s18, s18, s19
	s_lshl_b32 s19, s18, 3
	s_mul_i32 s18, s18, s16
	s_sub_i32 s16, 64, s19
	s_min_i32 s25, s16, 8
	s_sext_i32_i16 s16, s25
	v_cvt_f32_i32_e32 v1, s16
	s_sub_i32 s18, s17, s18
	s_sext_i32_i16 s17, s18
	v_cvt_f32_i32_e32 v2, s17
	v_rcp_iflag_f32_e32 v3, v1
	s_xor_b32 s16, s17, s16
	s_ashr_i32 s16, s16, 30
	s_or_b32 s26, s16, 1
	v_mul_f32_e32 v3, v2, v3
	v_trunc_f32_e32 v3, v3
	v_fma_f32 v2, -v3, v1, v2
	v_cvt_i32_f32_e32 v3, v3
	v_cmp_ge_f32_e64 s[16:17], |v2|, |v1|
	s_and_b64 s[16:17], s[16:17], exec
	s_cselect_b32 s16, s26, 0
	v_readfirstlane_b32 s17, v3
	s_add_i32 s16, s17, s16
	s_sext_i32_i16 s30, s16
	s_mul_i32 s16, s16, s25
	s_sub_i32 s16, s18, s16
	s_sext_i32_i16 s16, s16
	s_add_i32 s31, s19, s16
.Lmy_pro_join:
	s_andn2_b64 vcc, exec, s[4:5]
	s_cbranch_vccz .LBB0_47
.LBB0_43:
	s_cmp_lt_i32 s37, 4
	s_cbranch_scc1 .LBB0_130
